# v17 + redundant tile-start block barrier removed in all five GEMM tile prologues (the K-loop's final barrier already orders LDS reads before the next tile's first LDS-DMA)
# speedup vs baseline: 1.0037x; 1.0037x over previous
.LBB0_282:
	s_lshr_b32 s6, s18, 5
	s_mul_i32 s27, s6, 0x1112
	s_lshr_b32 s27, s27, 16
	s_mul_i32 s7, s27, 15
	s_sub_i32 s7, s6, s7
	s_lshl_b32 s6, s27, 3
	s_or_b32 s6, s6, s97
	s_mov_b32 s26, s6
	s_mov_b32 s27, s7
	s_lshl_b32 s7, s18, 7
	s_lshl_b32 s6, s6, 10
	s_and_b32 s7, s7, 0x380
	s_or_b32 s8, s6, s7
	s_lshl_b32 s6, s18, 4
	s_lshl_b32 s14, s27, 9
	s_and_b32 s6, s6, 0x180
	s_or_b32 s6, s14, s6
	s_ashr_i32 s9, s8, 31
	s_ashr_i32 s7, s6, 31
	s_lshl_b64 s[12:13], s[8:9], 10
	s_lshl_b64 s[16:17], s[6:7], 10
	v_readfirstlane_b32 s7, v199
	v_lshl_add_u64 v[0:1], v[152:153], 0, s[12:13]
	v_lshl_add_u64 v[2:3], v[154:155], 0, s[16:17]
	s_mov_b32 m0, s7
	v_readfirstlane_b32 s7, v200
	s_nop 0
	global_load_lds_dwordx4 v[0:1], off
	v_lshl_add_u64 v[4:5], v[2:3], 0, v[144:145]
	s_mov_b32 m0, s7
	s_mov_b64 s[12:13], 0x2000
	v_readfirstlane_b32 s7, v201
	global_load_lds_dwordx4 v[4:5], off
	v_lshl_add_u64 v[4:5], v[0:1], 0, s[12:13]
	s_mov_b32 m0, s7
	v_readfirstlane_b32 s7, v202
	global_load_lds_dwordx4 v[4:5], off
	v_lshl_add_u64 v[4:5], v[2:3], 0, v[146:147]
	s_mov_b32 m0, s7
	s_mov_b64 s[12:13], 0x4000
	v_readfirstlane_b32 s7, v203
	global_load_lds_dwordx4 v[4:5], off
	v_lshl_add_u64 v[4:5], v[0:1], 0, s[12:13]
	s_mov_b32 m0, s7
	v_readfirstlane_b32 s7, v204
	global_load_lds_dwordx4 v[4:5], off
	v_lshl_add_u64 v[4:5], v[2:3], 0, v[148:149]
	s_mov_b32 m0, s7
	s_mov_b64 s[12:13], 0x6000
	v_readfirstlane_b32 s7, v205
	global_load_lds_dwordx4 v[4:5], off
	v_lshl_add_u64 v[0:1], v[0:1], 0, s[12:13]
	s_mov_b32 m0, s7
	v_readfirstlane_b32 s7, v206
	global_load_lds_dwordx4 v[0:1], off
	v_lshl_add_u64 v[0:1], v[2:3], 0, v[150:151]
	s_mov_b32 m0, s7
	s_and_b32 s15, s19, 0x180
	global_load_lds_dwordx4 v[0:1], off
	s_or_b32 s12, s14, s15
	s_and_b32 s25, s21, 0x380
	s_ashr_i32 s13, s12, 31
	s_lshl_b32 s7, s26, 10
	s_lshl_b64 s[12:13], s[12:13], 10
	s_or_b32 s7, s7, s25
	s_mov_b32 s9, 0
	v_lshl_add_u64 v[160:161], v[156:157], 0, s[12:13]
	v_lshl_add_u64 v[162:163], v[158:159], 0, s[12:13]
	s_sub_i32 s12, s7, s9
	s_ashr_i32 s13, s12, 31
	s_lshl_b64 s[12:13], s[12:13], 10
	v_lshl_add_u64 v[164:165], v[152:153], 0, s[12:13]
	s_mov_b64 s[12:13], 0
	v_mov_b32_e32 v64, 0
	v_mov_b32_e32 v65, v143
	v_mov_b32_e32 v66, v143
	v_mov_b32_e32 v67, v143
	v_mov_b32_e32 v68, 0
	v_mov_b32_e32 v69, v143
	v_mov_b32_e32 v70, v143
	v_mov_b32_e32 v71, v143
	v_mov_b32_e32 v72, 0
	v_mov_b32_e32 v73, v143
	v_mov_b32_e32 v74, v143
	v_mov_b32_e32 v75, v143
	v_mov_b32_e32 v76, 0
	v_mov_b32_e32 v77, v143
	v_mov_b32_e32 v78, v143
	v_mov_b32_e32 v79, v143
	v_mov_b32_e32 v80, 0
	v_mov_b32_e32 v81, v143
	v_mov_b32_e32 v82, v143
	v_mov_b32_e32 v83, v143
	v_mov_b32_e32 v84, 0
	v_mov_b32_e32 v85, v143
	v_mov_b32_e32 v86, v143
	v_mov_b32_e32 v87, v143
	v_mov_b32_e32 v88, 0
	v_mov_b32_e32 v89, v143
	v_mov_b32_e32 v90, v143
	v_mov_b32_e32 v91, v143
	v_mov_b32_e32 v92, 0
	v_mov_b32_e32 v93, v143
	v_mov_b32_e32 v94, v143
	v_mov_b32_e32 v95, v143
	v_mov_b32_e32 v96, 0
	v_mov_b32_e32 v97, v143
	v_mov_b32_e32 v98, v143
	v_mov_b32_e32 v99, v143
	v_mov_b32_e32 v100, 0
	v_mov_b32_e32 v101, v143
	v_mov_b32_e32 v102, v143
	v_mov_b32_e32 v103, v143
	v_mov_b32_e32 v104, 0
	v_mov_b32_e32 v105, v143
	v_mov_b32_e32 v106, v143
	v_mov_b32_e32 v107, v143
	v_mov_b32_e32 v108, 0
	v_mov_b32_e32 v109, v143
	v_mov_b32_e32 v110, v143
	v_mov_b32_e32 v111, v143
	v_mov_b32_e32 v112, 0
	v_mov_b32_e32 v113, v143
	v_mov_b32_e32 v114, v143
	v_mov_b32_e32 v115, v143
	v_mov_b32_e32 v116, 0
	v_mov_b32_e32 v117, v143
	v_mov_b32_e32 v118, v143
	v_mov_b32_e32 v119, v143
	v_mov_b32_e32 v120, 0
	v_mov_b32_e32 v121, v143
	v_mov_b32_e32 v122, v143
	v_mov_b32_e32 v123, v143
	v_mov_b32_e32 v124, 0
	v_mov_b32_e32 v125, v143
	v_mov_b32_e32 v126, v143
	v_mov_b32_e32 v127, v143
	s_waitcnt vmcnt(0) lgkmcnt(0)
	s_barrier
	s_branch .LBB0_284

.LBB0_703:
	s_lshr_b32 s30, s33, 5
	s_and_b32 s46, s30, 1
	s_lshr_b32 s30, s30, 1
	s_lshl_b32 s30, s30, 3
	s_or_b32 s30, s30, s97
	s_mov_b32 s45, s30
	s_lshl_b32 s31, s33, 7
	s_lshl_b32 s30, s30, 10
	s_and_b32 s31, s31, 0x380
	s_or_b32 s30, s30, s31
	s_lshl_b32 s31, s33, 4
	s_lshl_b32 s47, s46, 9
	s_and_b32 s31, s31, 0x180
	s_or_b32 s34, s47, s31
	s_ashr_i32 s31, s30, 31
	s_lshl_b64 s[36:37], s[30:31], 11
	s_ashr_i32 s35, s34, 31
	s_lshl_b64 s[38:39], s[34:35], 11
	v_lshl_add_u64 v[0:1], v[106:107], 0, s[36:37]
	v_readfirstlane_b32 s36, v169
	v_lshl_add_u64 v[2:3], v[108:109], 0, s[38:39]
	s_mov_b32 m0, s36
	v_readfirstlane_b32 s36, v170
	s_nop 0
	global_load_lds_dwordx4 v[0:1], off
	v_lshl_add_u64 v[4:5], v[2:3], 0, v[88:89]
	s_mov_b32 m0, s36
	s_mov_b64 s[36:37], 0x4000
	global_load_lds_dwordx4 v[4:5], off
	v_lshl_add_u64 v[4:5], v[0:1], 0, s[36:37]
	v_readfirstlane_b32 s36, v171
	s_mov_b32 m0, s36
	v_readfirstlane_b32 s36, v177
	global_load_lds_dwordx4 v[4:5], off
	v_lshl_add_u64 v[4:5], v[2:3], 0, v[90:91]
	s_mov_b32 m0, s36
	s_mov_b64 s[36:37], 0x8000
	global_load_lds_dwordx4 v[4:5], off
	v_lshl_add_u64 v[4:5], v[0:1], 0, s[36:37]
	v_readfirstlane_b32 s36, v178
	s_mov_b32 m0, s36
	v_readfirstlane_b32 s36, v179
	global_load_lds_dwordx4 v[4:5], off
	s_mov_b32 m0, s36
	s_mov_b64 s[36:37], 0xc000
	v_lshl_add_u64 v[4:5], v[2:3], 0, v[92:93]
	v_lshl_add_u64 v[0:1], v[0:1], 0, s[36:37]
	v_readfirstlane_b32 s36, v180
	global_load_lds_dwordx4 v[4:5], off
	s_mov_b32 m0, s36
	v_readfirstlane_b32 s36, v181
	global_load_lds_dwordx4 v[0:1], off
	v_lshl_add_u64 v[0:1], v[2:3], 0, v[94:95]
	s_mov_b32 m0, s36
	s_and_b32 s24, s40, 0x180
	global_load_lds_dwordx4 v[0:1], off
	s_or_b32 s36, s47, s24
	s_ashr_i32 s37, s36, 31
	s_and_b32 s44, s42, 0x380
	s_lshl_b64 s[36:37], s[36:37], 11
	s_lshl_b32 s24, s45, 10
	v_lshl_add_u64 v[64:65], v[110:111], 0, s[36:37]
	v_lshl_add_u64 v[66:67], v[112:113], 0, s[36:37]
	s_or_b32 s24, s24, s44
	s_mov_b32 s36, 0
	s_sub_i32 s36, s24, s36
	s_ashr_i32 s37, s36, 31
	s_lshl_b64 s[36:37], s[36:37], 11
	v_lshl_add_u64 v[68:69], v[106:107], 0, s[36:37]
	s_mov_b64 s[36:37], 0
	s_mov_b32 s24, s25
	v_mov_b32_e32 v8, v87
	v_mov_b32_e32 v9, v87
	v_mov_b32_e32 v10, v87
	v_mov_b32_e32 v11, v87
	v_mov_b32_e32 v12, v87
	v_mov_b32_e32 v13, v87
	v_mov_b32_e32 v14, v87
	v_mov_b32_e32 v15, v87
	v_mov_b32_e32 v0, v87
	v_mov_b32_e32 v1, v87
	v_mov_b32_e32 v2, v87
	v_mov_b32_e32 v3, v87
	v_mov_b32_e32 v4, v87
	v_mov_b32_e32 v5, v87
	v_mov_b32_e32 v6, v87
	v_mov_b32_e32 v7, v87
	v_mov_b32_e32 v16, v87
	v_mov_b32_e32 v17, v87
	v_mov_b32_e32 v18, v87
	v_mov_b32_e32 v19, v87
	v_mov_b32_e32 v20, v87
	v_mov_b32_e32 v21, v87
	v_mov_b32_e32 v22, v87
	v_mov_b32_e32 v23, v87
	v_mov_b32_e32 v24, v87
	v_mov_b32_e32 v25, v87
	v_mov_b32_e32 v26, v87
	v_mov_b32_e32 v27, v87
	v_mov_b32_e32 v28, v87
	v_mov_b32_e32 v29, v87
	v_mov_b32_e32 v30, v87
	v_mov_b32_e32 v31, v87
	v_mov_b32_e32 v32, v87
	v_mov_b32_e32 v33, v87
	v_mov_b32_e32 v34, v87
	v_mov_b32_e32 v35, v87
	v_mov_b32_e32 v36, v87
	v_mov_b32_e32 v37, v87
	v_mov_b32_e32 v38, v87
	v_mov_b32_e32 v39, v87
	v_mov_b32_e32 v40, v87
	v_mov_b32_e32 v41, v87
	v_mov_b32_e32 v42, v87
	v_mov_b32_e32 v43, v87
	v_mov_b32_e32 v44, v87
	v_mov_b32_e32 v45, v87
	v_mov_b32_e32 v46, v87
	v_mov_b32_e32 v47, v87
	v_mov_b32_e32 v48, v87
	v_mov_b32_e32 v49, v87
	v_mov_b32_e32 v50, v87
	v_mov_b32_e32 v51, v87
	v_mov_b32_e32 v52, v87
	v_mov_b32_e32 v53, v87
	v_mov_b32_e32 v54, v87
	v_mov_b32_e32 v55, v87
	v_mov_b32_e32 v56, v87
	v_mov_b32_e32 v57, v87
	v_mov_b32_e32 v58, v87
	v_mov_b32_e32 v59, v87
	v_mov_b32_e32 v60, v87
	v_mov_b32_e32 v61, v87
	v_mov_b32_e32 v62, v87
	v_mov_b32_e32 v63, v87
	s_waitcnt vmcnt(0) lgkmcnt(0)
	s_barrier
	s_branch .LBB0_705

.LBB0_707:
	v_add_u32_e32 v68, s30, v162
	v_or_b32_e32 v64, s34, v165
	v_ashrrev_i32_e32 v69, 31, v68
	v_readlane_b32 s44, v247, 2
	v_ashrrev_i32_e32 v65, 31, v64
	v_lshlrev_b64 v[66:67], 12, v[68:69]
	v_readlane_b32 s48, v247, 6
	v_readlane_b32 s49, v247, 7
	s_lshl_b64 s[30:31], s[30:31], 9
	v_readlane_b32 s76, v247, 61
	v_lshl_add_u64 v[70:71], s[48:49], 0, v[66:67]
	v_lshlrev_b64 v[66:67], 1, v[64:65]
	v_lshl_add_u64 v[64:65], v[70:71], 0, v[66:67]
	global_load_dwordx4 v[114:117], v[64:65], off offset:16
	global_load_dwordx4 v[118:121], v[64:65], off
	v_or_b32_e32 v222, 16, v68
	v_ashrrev_i32_e32 v223, 31, v222
	v_lshlrev_b64 v[224:225], 12, v[222:223]
	v_lshl_add_u64 v[224:225], s[48:49], 0, v[224:225]
	v_lshl_add_u64 v[216:217], v[224:225], 0, v[66:67]
	v_or_b32_e32 v222, 32, v68
	v_ashrrev_i32_e32 v223, 31, v222
	v_lshlrev_b64 v[224:225], 12, v[222:223]
	v_lshl_add_u64 v[224:225], s[48:49], 0, v[224:225]
	v_lshl_add_u64 v[218:219], v[224:225], 0, v[66:67]
	v_or_b32_e32 v222, 48, v68
	v_ashrrev_i32_e32 v223, 31, v222
	v_lshlrev_b64 v[224:225], 12, v[222:223]
	v_lshl_add_u64 v[224:225], s[48:49], 0, v[224:225]
	v_lshl_add_u64 v[220:221], v[224:225], 0, v[66:67]
	global_load_dwordx4 v[192:195], v[216:217], off offset:16
	global_load_dwordx4 v[196:199], v[216:217], off
	global_load_dwordx4 v[200:203], v[218:219], off offset:16
	global_load_dwordx4 v[204:207], v[218:219], off
	global_load_dwordx4 v[208:211], v[220:221], off offset:16
	global_load_dwordx4 v[212:215], v[220:221], off
	v_readlane_b32 s50, v247, 8
	v_readlane_b32 s51, v247, 9
	s_add_u32 s36, s72, s30
	v_readlane_b32 s90, v248, 11
	v_readlane_b32 s91, v248, 12
	s_addc_u32 s37, s73, s31
	s_lshl_b64 s[30:31], s[34:35], 9
	s_mov_b64 s[50:51], s[90:91]
	s_add_u32 s30, s50, s30
	s_addc_u32 s31, s51, s31
	v_readfirstlane_b32 s24, v169
	s_mov_b32 m0, s24
	v_readfirstlane_b32 s24, v170
	s_mov_b64 s[34:35], 0x1000
	v_readlane_b32 s45, v247, 3
	v_readlane_b32 s46, v247, 4
	v_readlane_b32 s47, v247, 5
	v_readlane_b32 s77, v247, 62
	v_readlane_b32 s78, v247, 63
	v_readlane_b32 s79, v248, 0
	v_readlane_b32 s80, v248, 1
	v_readlane_b32 s81, v248, 2
	v_readlane_b32 s82, v248, 3
	v_readlane_b32 s83, v248, 4
	v_readlane_b32 s84, v248, 5
	v_readlane_b32 s85, v248, 6
	v_readlane_b32 s86, v248, 7
	v_readlane_b32 s87, v248, 8
	v_readlane_b32 s88, v248, 9
	v_readlane_b32 s89, v248, 10
	s_waitcnt vmcnt(6)
	v_lshlrev_b32_e32 v70, 16, v118
	v_and_b32_e32 v71, 0xffff0000, v118
	v_pk_mul_f32 v[60:61], v[60:61], v[70:71]
	v_lshlrev_b32_e32 v70, 16, v119
	v_and_b32_e32 v71, 0xffff0000, v119
	v_pk_mul_f32 v[62:63], v[62:63], v[70:71]
	v_lshlrev_b32_e32 v70, 16, v120
	v_and_b32_e32 v71, 0xffff0000, v120
	v_pk_mul_f32 v[56:57], v[56:57], v[70:71]
	v_lshlrev_b32_e32 v70, 16, v121
	v_and_b32_e32 v71, 0xffff0000, v121
	v_pk_mul_f32 v[58:59], v[58:59], v[70:71]
	v_lshlrev_b32_e32 v70, 16, v114
	v_and_b32_e32 v71, 0xffff0000, v114
	v_pk_mul_f32 v[52:53], v[52:53], v[70:71]
	v_lshlrev_b32_e32 v70, 16, v115
	v_and_b32_e32 v71, 0xffff0000, v115
	v_pk_mul_f32 v[54:55], v[54:55], v[70:71]
	v_lshlrev_b32_e32 v70, 16, v116
	v_and_b32_e32 v71, 0xffff0000, v116
	v_pk_mul_f32 v[70:71], v[48:49], v[70:71]
	v_lshlrev_b32_e32 v48, 16, v117
	v_and_b32_e32 v49, 0xffff0000, v117
	v_pk_mul_f32 v[114:115], v[50:51], v[48:49]
	v_lshlrev_b64 v[48:49], 11, v[68:69]
	v_lshl_add_u64 v[48:49], s[70:71], 0, v[48:49]
	v_cvt_pk_bf16_f32 v50, v56, v57
	v_or_b32_e32 v56, 16, v68
	v_lshl_add_u64 v[120:121], v[48:49], 0, v[66:67]
	v_cvt_pk_bf16_f32 v48, v60, v61
	v_cvt_pk_bf16_f32 v49, v62, v63
	v_cvt_pk_bf16_f32 v51, v58, v59
	v_ashrrev_i32_e32 v57, 31, v56
	v_cvt_pk_bf16_f32 v52, v52, v53
	v_cvt_pk_bf16_f32 v53, v54, v55
	v_cvt_pk_bf16_f32 v54, v70, v71
	v_cvt_pk_bf16_f32 v55, v114, v115
	global_store_dwordx4 v[120:121], v[48:51], off
	global_store_dwordx4 v[120:121], v[52:55], off offset:16
	s_nop 0
	v_lshlrev_b64 v[48:49], 12, v[56:57]
	v_lshl_add_u64 v[48:49], s[48:49], 0, v[48:49]
	v_lshl_add_u64 v[126:127], v[48:49], 0, v[66:67]
	s_waitcnt vmcnt(6)
	v_mov_b32_e32 v48, v192
	v_mov_b32_e32 v49, v193
	v_mov_b32_e32 v50, v194
	v_mov_b32_e32 v51, v195
	v_mov_b32_e32 v52, v196
	v_mov_b32_e32 v53, v197
	v_mov_b32_e32 v54, v198
	v_mov_b32_e32 v55, v199
	v_lshlrev_b32_e32 v58, 16, v52
	v_and_b32_e32 v59, 0xffff0000, v52
	v_lshlrev_b32_e32 v52, 16, v53
	v_and_b32_e32 v53, 0xffff0000, v53
	v_pk_mul_f32 v[46:47], v[46:47], v[52:53]
	v_lshlrev_b32_e32 v52, 16, v54
	v_and_b32_e32 v53, 0xffff0000, v54
	v_pk_mul_f32 v[40:41], v[40:41], v[52:53]
	v_lshlrev_b32_e32 v52, 16, v55
	v_and_b32_e32 v53, 0xffff0000, v55
	v_pk_mul_f32 v[42:43], v[42:43], v[52:53]
	v_lshlrev_b32_e32 v52, 16, v48
	v_and_b32_e32 v53, 0xffff0000, v48
	v_lshlrev_b32_e32 v48, 16, v49
	v_and_b32_e32 v49, 0xffff0000, v49
	v_pk_mul_f32 v[38:39], v[38:39], v[48:49]
	v_lshlrev_b32_e32 v48, 16, v50
	v_and_b32_e32 v49, 0xffff0000, v50
	v_pk_mul_f32 v[48:49], v[32:33], v[48:49]
	v_lshlrev_b32_e32 v32, 16, v51
	v_and_b32_e32 v33, 0xffff0000, v51
	v_pk_mul_f32 v[50:51], v[34:35], v[32:33]
	v_lshlrev_b64 v[32:33], 11, v[56:57]
	v_pk_mul_f32 v[44:45], v[44:45], v[58:59]
	v_lshl_add_u64 v[32:33], s[70:71], 0, v[32:33]
	v_cvt_pk_bf16_f32 v34, v40, v41
	v_or_b32_e32 v40, 32, v68
	v_pk_mul_f32 v[36:37], v[36:37], v[52:53]
	v_lshl_add_u64 v[118:119], v[32:33], 0, v[66:67]
	v_cvt_pk_bf16_f32 v32, v44, v45
	v_cvt_pk_bf16_f32 v33, v46, v47
	v_cvt_pk_bf16_f32 v35, v42, v43
	v_ashrrev_i32_e32 v41, 31, v40
	v_cvt_pk_bf16_f32 v36, v36, v37
	v_cvt_pk_bf16_f32 v37, v38, v39
	v_cvt_pk_bf16_f32 v38, v48, v49
	v_cvt_pk_bf16_f32 v39, v50, v51
	global_store_dwordx4 v[118:119], v[32:35], off
	global_store_dwordx4 v[118:119], v[36:39], off offset:16
	s_nop 0
	v_lshlrev_b64 v[32:33], 12, v[40:41]
	v_lshl_add_u64 v[32:33], s[48:49], 0, v[32:33]
	v_lshl_add_u64 v[124:125], v[32:33], 0, v[66:67]
	s_waitcnt vmcnt(6)
	v_mov_b32_e32 v32, v200
	v_mov_b32_e32 v33, v201
	v_mov_b32_e32 v34, v202
	v_mov_b32_e32 v35, v203
	v_mov_b32_e32 v36, v204
	v_mov_b32_e32 v37, v205
	v_mov_b32_e32 v38, v206
	v_mov_b32_e32 v39, v207
	v_lshlrev_b32_e32 v42, 16, v36
	v_and_b32_e32 v43, 0xffff0000, v36
	v_lshlrev_b32_e32 v36, 16, v37
	v_and_b32_e32 v37, 0xffff0000, v37
	v_pk_mul_f32 v[30:31], v[30:31], v[36:37]
	v_lshlrev_b32_e32 v36, 16, v38
	v_and_b32_e32 v37, 0xffff0000, v38
	v_pk_mul_f32 v[24:25], v[24:25], v[36:37]
	v_lshlrev_b32_e32 v36, 16, v39
	v_and_b32_e32 v37, 0xffff0000, v39
	v_pk_mul_f32 v[26:27], v[26:27], v[36:37]
	v_lshlrev_b32_e32 v36, 16, v32
	v_and_b32_e32 v37, 0xffff0000, v32
	v_lshlrev_b32_e32 v32, 16, v33
	v_and_b32_e32 v33, 0xffff0000, v33
	v_pk_mul_f32 v[22:23], v[22:23], v[32:33]
	v_lshlrev_b32_e32 v32, 16, v34
	v_and_b32_e32 v33, 0xffff0000, v34
	v_pk_mul_f32 v[32:33], v[16:17], v[32:33]
	v_lshlrev_b32_e32 v16, 16, v35
	v_and_b32_e32 v17, 0xffff0000, v35
	v_pk_mul_f32 v[34:35], v[18:19], v[16:17]
	v_lshlrev_b64 v[16:17], 11, v[40:41]
	v_pk_mul_f32 v[28:29], v[28:29], v[42:43]
	v_lshl_add_u64 v[16:17], s[70:71], 0, v[16:17]
	v_cvt_pk_bf16_f32 v18, v24, v25
	v_or_b32_e32 v24, 48, v68
	v_pk_mul_f32 v[20:21], v[20:21], v[36:37]
	v_lshl_add_u64 v[116:117], v[16:17], 0, v[66:67]
	v_cvt_pk_bf16_f32 v16, v28, v29
	v_cvt_pk_bf16_f32 v17, v30, v31
	v_cvt_pk_bf16_f32 v19, v26, v27
	v_ashrrev_i32_e32 v25, 31, v24
	v_cvt_pk_bf16_f32 v20, v20, v21
	v_cvt_pk_bf16_f32 v21, v22, v23
	v_cvt_pk_bf16_f32 v22, v32, v33
	v_cvt_pk_bf16_f32 v23, v34, v35
	global_store_dwordx4 v[116:117], v[16:19], off
	global_store_dwordx4 v[116:117], v[20:23], off offset:16
	v_lshl_add_u64 v[68:69], s[30:31], 0, v[98:99]
	v_lshlrev_b64 v[16:17], 12, v[24:25]
	v_lshl_add_u64 v[16:17], s[48:49], 0, v[16:17]
	v_lshl_add_u64 v[122:123], v[16:17], 0, v[66:67]
	s_waitcnt vmcnt(6)
	v_mov_b32_e32 v16, v208
	v_mov_b32_e32 v17, v209
	v_mov_b32_e32 v18, v210
	v_mov_b32_e32 v19, v211
	v_mov_b32_e32 v20, v212
	v_mov_b32_e32 v21, v213
	v_mov_b32_e32 v22, v214
	v_mov_b32_e32 v23, v215
	v_lshlrev_b32_e32 v26, 16, v20
	v_and_b32_e32 v27, 0xffff0000, v20
	v_lshlrev_b32_e32 v20, 16, v21
	v_and_b32_e32 v21, 0xffff0000, v21
	v_pk_mul_f32 v[6:7], v[6:7], v[20:21]
	v_lshlrev_b32_e32 v20, 16, v22
	v_and_b32_e32 v21, 0xffff0000, v22
	v_pk_mul_f32 v[20:21], v[0:1], v[20:21]
	v_lshlrev_b32_e32 v0, 16, v23
	v_and_b32_e32 v1, 0xffff0000, v23
	v_pk_mul_f32 v[22:23], v[2:3], v[0:1]
	v_lshlrev_b32_e32 v0, 16, v16
	v_and_b32_e32 v1, 0xffff0000, v16
	v_pk_mul_f32 v[12:13], v[12:13], v[0:1]
	v_lshlrev_b32_e32 v0, 16, v17
	v_and_b32_e32 v1, 0xffff0000, v17
	v_pk_mul_f32 v[14:15], v[14:15], v[0:1]
	v_lshlrev_b32_e32 v0, 16, v18
	v_and_b32_e32 v1, 0xffff0000, v18
	v_pk_mul_f32 v[8:9], v[8:9], v[0:1]
	v_lshlrev_b32_e32 v0, 16, v19
	v_and_b32_e32 v1, 0xffff0000, v19
	v_pk_mul_f32 v[10:11], v[10:11], v[0:1]
	v_lshlrev_b64 v[0:1], 11, v[24:25]
	v_pk_mul_f32 v[4:5], v[4:5], v[26:27]
	v_lshl_add_u64 v[0:1], s[70:71], 0, v[0:1]
	v_lshl_add_u64 v[114:115], v[0:1], 0, v[66:67]
	v_cvt_pk_bf16_f32 v0, v4, v5
	v_cvt_pk_bf16_f32 v1, v6, v7
	v_cvt_pk_bf16_f32 v2, v20, v21
	v_cvt_pk_bf16_f32 v3, v22, v23
	v_lshl_add_u64 v[66:67], s[36:37], 0, v[96:97]
	v_cvt_pk_bf16_f32 v4, v12, v13
	v_cvt_pk_bf16_f32 v5, v14, v15
	v_cvt_pk_bf16_f32 v6, v8, v9
	v_cvt_pk_bf16_f32 v7, v10, v11
	global_store_dwordx4 v[114:115], v[0:3], off
	global_store_dwordx4 v[114:115], v[4:7], off offset:16
	s_nop 0
	global_load_lds_dwordx4 v[66:67], off
	v_lshl_add_u64 v[0:1], v[68:69], 0, v[100:101]
	s_mov_b32 m0, s24
	v_readfirstlane_b32 s24, v171
	global_load_lds_dwordx4 v[0:1], off
	v_lshl_add_u64 v[2:3], v[66:67], 0, s[34:35]
	s_mov_b32 m0, s24
	v_readfirstlane_b32 s24, v177
	global_load_lds_dwordx4 v[2:3], off
	v_lshl_add_u64 v[2:3], v[68:69], 0, v[102:103]
	s_mov_b32 m0, s24
	v_readfirstlane_b32 s24, v178
	global_load_lds_dwordx4 v[2:3], off
	v_lshl_add_u64 v[2:3], v[66:67], 0, s[12:13]
	s_mov_b32 m0, s24
	v_readfirstlane_b32 s24, v179
	global_load_lds_dwordx4 v[2:3], off
	v_lshl_add_u64 v[0:1], v[0:1], 0, s[14:15]
	s_mov_b32 m0, s24
	v_readfirstlane_b32 s24, v180
	global_load_lds_dwordx4 v[0:1], off
	v_lshl_add_u64 v[0:1], v[66:67], 0, s[16:17]
	s_mov_b32 m0, s24
	v_readfirstlane_b32 s24, v181
	global_load_lds_dwordx4 v[0:1], off
	v_lshl_add_u64 v[0:1], v[68:69], 0, v[104:105]
	s_mov_b32 m0, s24
	v_lshl_add_u64 v[2:3], s[30:31], 0, v[102:103]
	global_load_lds_dwordx4 v[0:1], off
	v_lshl_add_u64 v[0:1], s[30:31], 0, v[100:101]
	v_lshl_add_u64 v[0:1], v[0:1], 0, v[98:99]
	v_lshl_add_u64 v[140:141], v[0:1], 0, s[8:9]
	v_lshl_add_u64 v[148:149], v[0:1], 0, s[20:21]
	v_lshl_add_u64 v[0:1], s[30:31], 0, v[104:105]
	v_lshl_add_u64 v[2:3], v[2:3], 0, v[98:99]
	v_lshl_add_u64 v[0:1], v[0:1], 0, v[98:99]
	v_mov_b32_e32 v8, 0
	v_lshl_add_u64 v[70:71], v[66:67], 0, s[8:9]
	v_lshl_add_u64 v[142:143], v[66:67], 0, s[18:19]
	v_lshl_add_u64 v[144:145], v[2:3], 0, s[8:9]
	v_lshl_add_u64 v[146:147], v[66:67], 0, s[10:11]
	v_lshl_add_u64 v[150:151], v[66:67], 0, s[22:23]
	v_lshl_add_u64 v[152:153], v[0:1], 0, s[8:9]
	s_mov_b32 s24, 0
	s_mov_b64 s[30:31], -1
	v_mov_b32_e32 v9, v8
	v_mov_b32_e32 v10, v8
	v_mov_b32_e32 v11, v8
	v_mov_b32_e32 v12, v8
	v_mov_b32_e32 v13, v8
	v_mov_b32_e32 v14, v8
	v_mov_b32_e32 v15, v8
	v_mov_b32_e32 v0, v8
	v_mov_b32_e32 v1, v8
	v_mov_b32_e32 v2, v8
	v_mov_b32_e32 v3, v8
	v_mov_b32_e32 v4, v8
	v_mov_b32_e32 v5, v8
	v_mov_b32_e32 v6, v8
	v_mov_b32_e32 v7, v8
	v_mov_b32_e32 v16, v8
	v_mov_b32_e32 v17, v8
	v_mov_b32_e32 v18, v8
	v_mov_b32_e32 v19, v8
	v_mov_b32_e32 v20, v8
	v_mov_b32_e32 v21, v8
	v_mov_b32_e32 v22, v8
	v_mov_b32_e32 v23, v8
	v_mov_b32_e32 v24, v8
	v_mov_b32_e32 v25, v8
	v_mov_b32_e32 v26, v8
	v_mov_b32_e32 v27, v8
	v_mov_b32_e32 v28, v8
	v_mov_b32_e32 v29, v8
	v_mov_b32_e32 v30, v8
	v_mov_b32_e32 v31, v8
	v_mov_b32_e32 v32, v8
	v_mov_b32_e32 v33, v8
	v_mov_b32_e32 v34, v8
	v_mov_b32_e32 v35, v8
	v_mov_b32_e32 v36, v8
	v_mov_b32_e32 v37, v8
	v_mov_b32_e32 v38, v8
	v_mov_b32_e32 v39, v8
	v_mov_b32_e32 v40, v8
	v_mov_b32_e32 v41, v8
	v_mov_b32_e32 v42, v8
	v_mov_b32_e32 v43, v8
	v_mov_b32_e32 v44, v8
	v_mov_b32_e32 v45, v8
	v_mov_b32_e32 v46, v8
	v_mov_b32_e32 v47, v8
	v_mov_b32_e32 v48, v8
	v_mov_b32_e32 v49, v8
	v_mov_b32_e32 v50, v8
	v_mov_b32_e32 v51, v8
	v_mov_b32_e32 v52, v8
	v_mov_b32_e32 v53, v8
	v_mov_b32_e32 v54, v8
	v_mov_b32_e32 v55, v8
	v_mov_b32_e32 v56, v8
	v_mov_b32_e32 v57, v8
	v_mov_b32_e32 v58, v8
	v_mov_b32_e32 v59, v8
	v_mov_b32_e32 v60, v8
	v_mov_b32_e32 v61, v8
	v_mov_b32_e32 v62, v8
	v_mov_b32_e32 v63, v8
	s_waitcnt vmcnt(0) lgkmcnt(0)
	s_barrier
	s_branch .LBB0_709

.LBB0_768:
	s_lshr_b32 s30, s33, 5
	s_and_b32 s48, s30, 1
	s_lshr_b32 s30, s30, 1
	s_lshl_b32 s30, s30, 3
	s_or_b32 s30, s30, s97
	s_mov_b32 s47, s30
	s_lshl_b32 s31, s33, 7
	s_lshl_b32 s30, s30, 10
	s_and_b32 s31, s31, 0x380
	s_or_b32 s30, s30, s31
	s_lshl_b32 s31, s33, 4
	s_lshl_b32 s49, s48, 9
	s_and_b32 s31, s31, 0x180
	s_or_b32 s34, s49, s31
	s_ashr_i32 s31, s30, 31
	s_ashr_i32 s35, s34, 31
	s_lshl_b64 s[36:37], s[30:31], 11
	s_lshl_b64 s[38:39], s[34:35], 11
	v_readfirstlane_b32 s31, v112
	v_lshl_add_u64 v[0:1], v[86:87], 0, s[36:37]
	v_lshl_add_u64 v[2:3], v[88:89], 0, s[38:39]
	s_mov_b32 m0, s31
	v_readfirstlane_b32 s31, v113
	s_nop 0
	global_load_lds_dwordx4 v[0:1], off
	v_lshl_add_u64 v[4:5], v[2:3], 0, v[64:65]
	s_mov_b32 m0, s31
	v_readfirstlane_b32 s31, v114
	global_load_lds_dwordx4 v[4:5], off
	v_lshl_add_u64 v[4:5], v[0:1], 0, s[0:1]
	s_mov_b32 m0, s31
	v_readfirstlane_b32 s31, v115
	global_load_lds_dwordx4 v[4:5], off
	v_lshl_add_u64 v[4:5], v[2:3], 0, v[66:67]
	s_mov_b32 m0, s31
	v_readfirstlane_b32 s31, v116
	global_load_lds_dwordx4 v[4:5], off
	v_lshl_add_u64 v[4:5], v[0:1], 0, s[2:3]
	s_mov_b32 m0, s31
	v_readfirstlane_b32 s31, v117
	global_load_lds_dwordx4 v[4:5], off
	v_lshl_add_u64 v[4:5], v[2:3], 0, v[68:69]
	s_mov_b32 m0, s31
	v_readfirstlane_b32 s31, v118
	global_load_lds_dwordx4 v[4:5], off
	v_lshl_add_u64 v[0:1], v[0:1], 0, s[4:5]
	s_mov_b32 m0, s31
	v_readfirstlane_b32 s31, v119
	global_load_lds_dwordx4 v[0:1], off
	v_lshl_add_u64 v[0:1], v[2:3], 0, v[70:71]
	s_mov_b32 m0, s31
	s_and_b32 s45, s41, 0x180
	global_load_lds_dwordx4 v[0:1], off
	s_or_b32 s36, s49, s45
	s_and_b32 s46, s43, 0x380
	s_ashr_i32 s37, s36, 31
	s_lshl_b32 s31, s47, 10
	s_lshl_b64 s[36:37], s[36:37], 11
	s_or_b32 s31, s31, s46
	s_mov_b32 s35, 0
	s_waitcnt vmcnt(0)
	v_lshl_add_u64 v[94:95], v[90:91], 0, s[36:37]
	v_lshl_add_u64 v[96:97], v[92:93], 0, s[36:37]
	s_sub_i32 s36, s31, s35
	s_ashr_i32 s37, s36, 31
	s_lshl_b64 s[36:37], s[36:37], 11
	v_lshl_add_u64 v[98:99], v[86:87], 0, s[36:37]
	s_mov_b64 s[36:37], 0
	s_mov_b32 s31, 0
	v_mov_b32_e32 v8, 0
	v_mov_b32_e32 v9, v65
	v_mov_b32_e32 v10, v65
	v_mov_b32_e32 v11, v65
	v_mov_b32_e32 v16, 0
	v_mov_b32_e32 v17, v65
	v_mov_b32_e32 v18, v65
	v_mov_b32_e32 v19, v65
	v_mov_b32_e32 v0, 0
	v_mov_b32_e32 v1, v65
	v_mov_b32_e32 v2, v65
	v_mov_b32_e32 v3, v65
	v_mov_b32_e32 v4, 0
	v_mov_b32_e32 v5, v65
	v_mov_b32_e32 v6, v65
	v_mov_b32_e32 v7, v65
	v_mov_b32_e32 v12, 0
	v_mov_b32_e32 v13, v65
	v_mov_b32_e32 v14, v65
	v_mov_b32_e32 v15, v65
	v_mov_b32_e32 v20, 0
	v_mov_b32_e32 v21, v65
	v_mov_b32_e32 v22, v65
	v_mov_b32_e32 v23, v65
	v_mov_b32_e32 v24, 0
	v_mov_b32_e32 v25, v65
	v_mov_b32_e32 v26, v65
	v_mov_b32_e32 v27, v65
	v_mov_b32_e32 v28, 0
	v_mov_b32_e32 v29, v65
	v_mov_b32_e32 v30, v65
	v_mov_b32_e32 v31, v65
	v_mov_b32_e32 v32, 0
	v_mov_b32_e32 v33, v65
	v_mov_b32_e32 v34, v65
	v_mov_b32_e32 v35, v65
	v_mov_b32_e32 v36, 0
	v_mov_b32_e32 v37, v65
	v_mov_b32_e32 v38, v65
	v_mov_b32_e32 v39, v65
	v_mov_b32_e32 v40, 0
	v_mov_b32_e32 v41, v65
	v_mov_b32_e32 v42, v65
	v_mov_b32_e32 v43, v65
	v_mov_b32_e32 v44, 0
	v_mov_b32_e32 v45, v65
	v_mov_b32_e32 v46, v65
	v_mov_b32_e32 v47, v65
	v_mov_b32_e32 v48, 0
	v_mov_b32_e32 v49, v65
	v_mov_b32_e32 v50, v65
	v_mov_b32_e32 v51, v65
	v_mov_b32_e32 v52, 0
	v_mov_b32_e32 v53, v65
	v_mov_b32_e32 v54, v65
	v_mov_b32_e32 v55, v65
	v_mov_b32_e32 v56, 0
	v_mov_b32_e32 v57, v65
	v_mov_b32_e32 v58, v65
	v_mov_b32_e32 v59, v65
	v_mov_b32_e32 v60, 0
	v_mov_b32_e32 v61, v65
	v_mov_b32_e32 v62, v65
	v_mov_b32_e32 v63, v65
	s_waitcnt lgkmcnt(0)
	s_barrier
	s_branch .LBB0_770

.LBB0_886:
	s_lshr_b32 s26, s33, 5
	s_and_b32 s43, s26, 3
	s_lshr_b32 s26, s26, 2
	s_lshl_b32 s26, s26, 3
	s_or_b32 s26, s26, s97
	s_mov_b32 s42, s26
	s_lshl_b32 s27, s33, 7
	s_lshl_b32 s26, s26, 10
	s_and_b32 s27, s27, 0x380
	s_or_b32 s26, s26, s27
	s_lshl_b32 s27, s33, 4
	s_lshl_b32 s44, s43, 9
	s_and_b32 s27, s27, 0x180
	s_or_b32 s28, s44, s27
	s_ashr_i32 s27, s26, 31
	s_ashr_i32 s29, s28, 31
	s_lshl_b64 s[30:31], s[26:27], 11
	s_lshl_b64 s[34:35], s[28:29], 11
	v_readfirstlane_b32 s27, v73
	v_lshl_add_u64 v[0:1], v[86:87], 0, s[30:31]
	v_lshl_add_u64 v[2:3], v[88:89], 0, s[34:35]
	s_mov_b32 m0, s27
	v_readfirstlane_b32 s27, v77
	s_nop 0
	global_load_lds_dwordx4 v[0:1], off
	v_lshl_add_u64 v[4:5], v[2:3], 0, v[64:65]
	s_mov_b32 m0, s27
	v_readfirstlane_b32 s27, v111
	global_load_lds_dwordx4 v[4:5], off
	v_lshl_add_u64 v[4:5], v[0:1], 0, s[0:1]
	s_mov_b32 m0, s27
	v_readfirstlane_b32 s27, v112
	global_load_lds_dwordx4 v[4:5], off
	v_lshl_add_u64 v[4:5], v[2:3], 0, v[66:67]
	s_mov_b32 m0, s27
	v_readfirstlane_b32 s27, v113
	global_load_lds_dwordx4 v[4:5], off
	v_lshl_add_u64 v[4:5], v[0:1], 0, s[2:3]
	s_mov_b32 m0, s27
	v_readfirstlane_b32 s27, v114
	global_load_lds_dwordx4 v[4:5], off
	v_lshl_add_u64 v[4:5], v[2:3], 0, v[68:69]
	s_mov_b32 m0, s27
	v_readfirstlane_b32 s27, v115
	global_load_lds_dwordx4 v[4:5], off
	v_lshl_add_u64 v[0:1], v[0:1], 0, s[4:5]
	s_mov_b32 m0, s27
	v_readfirstlane_b32 s27, v116
	global_load_lds_dwordx4 v[0:1], off
	v_lshl_add_u64 v[0:1], v[2:3], 0, v[70:71]
	s_mov_b32 m0, s27
	s_and_b32 s40, s36, 0x180
	global_load_lds_dwordx4 v[0:1], off
	s_or_b32 s30, s44, s40
	s_and_b32 s41, s38, 0x380
	s_ashr_i32 s31, s30, 31
	s_lshl_b32 s27, s42, 10
	s_lshl_b64 s[30:31], s[30:31], 11
	s_or_b32 s27, s27, s41
	s_mov_b32 s29, 0
	v_lshl_add_u64 v[94:95], v[90:91], 0, s[30:31]
	v_lshl_add_u64 v[96:97], v[92:93], 0, s[30:31]
	s_sub_i32 s30, s27, s29
	s_ashr_i32 s31, s30, 31
	s_lshl_b64 s[30:31], s[30:31], 11
	v_lshl_add_u64 v[98:99], v[86:87], 0, s[30:31]
	s_mov_b32 s27, 0
	s_mov_b64 s[30:31], 0
	v_mov_b32_e32 v24, 0
	v_mov_b32_e32 v25, v65
	v_mov_b32_e32 v26, v65
	v_mov_b32_e32 v27, v65
	v_mov_b32_e32 v28, 0
	v_mov_b32_e32 v29, v65
	v_mov_b32_e32 v30, v65
	v_mov_b32_e32 v31, v65
	v_mov_b32_e32 v0, 0
	v_mov_b32_e32 v1, v65
	v_mov_b32_e32 v2, v65
	v_mov_b32_e32 v3, v65
	v_mov_b32_e32 v4, 0
	v_mov_b32_e32 v5, v65
	v_mov_b32_e32 v6, v65
	v_mov_b32_e32 v7, v65
	v_mov_b32_e32 v8, 0
	v_mov_b32_e32 v9, v65
	v_mov_b32_e32 v10, v65
	v_mov_b32_e32 v11, v65
	v_mov_b32_e32 v12, 0
	v_mov_b32_e32 v13, v65
	v_mov_b32_e32 v14, v65
	v_mov_b32_e32 v15, v65
	v_mov_b32_e32 v16, 0
	v_mov_b32_e32 v17, v65
	v_mov_b32_e32 v18, v65
	v_mov_b32_e32 v19, v65
	v_mov_b32_e32 v20, 0
	v_mov_b32_e32 v21, v65
	v_mov_b32_e32 v22, v65
	v_mov_b32_e32 v23, v65
	v_mov_b32_e32 v32, 0
	v_mov_b32_e32 v33, v65
	v_mov_b32_e32 v34, v65
	v_mov_b32_e32 v35, v65
	v_mov_b32_e32 v36, 0
	v_mov_b32_e32 v37, v65
	v_mov_b32_e32 v38, v65
	v_mov_b32_e32 v39, v65
	v_mov_b32_e32 v40, 0
	v_mov_b32_e32 v41, v65
	v_mov_b32_e32 v42, v65
	v_mov_b32_e32 v43, v65
	v_mov_b32_e32 v44, 0
	v_mov_b32_e32 v45, v65
	v_mov_b32_e32 v46, v65
	v_mov_b32_e32 v47, v65
	v_mov_b32_e32 v48, 0
	v_mov_b32_e32 v49, v65
	v_mov_b32_e32 v50, v65
	v_mov_b32_e32 v51, v65
	v_mov_b32_e32 v52, 0
	v_mov_b32_e32 v53, v65
	v_mov_b32_e32 v54, v65
	v_mov_b32_e32 v55, v65
	v_mov_b32_e32 v56, 0
	v_mov_b32_e32 v57, v65
	v_mov_b32_e32 v58, v65
	v_mov_b32_e32 v59, v65
	v_mov_b32_e32 v60, 0
	v_mov_b32_e32 v61, v65
	v_mov_b32_e32 v62, v65
	v_mov_b32_e32 v63, v65
	s_waitcnt vmcnt(0) lgkmcnt(0)
	s_barrier
	s_branch .LBB0_888
